# P4 fused epilogue: residual x loads prefetched four groups ahead (counted vmcnt), on top of the lane-permuted P1 epilogue stores, row-contiguous side-task loads and counted seam waits
# speedup vs baseline: 1.0007x; 1.0007x over previous
;     __device__ __forceinline__ void fused(Acc& acc, const Unit& u, int wr, int wc, int fr, int fq, LAS unsigned char* lds, int wid, int lane) const {
;     ...
;         const size_t o0 = (size_t)(u.pm * 256 + wr * 64 + fr) * DM + u.pn * 256 + wc * 32 + 4 * fq;
; #pragma unroll
;         for (int ai = 0; ai < 2; ++ai)
; #pragma unroll
;             for (int m = 0; m < 4; ++m) { float s = 0.f; const size_t o = o0 + (size_t)(ai * 128 + m * 16) * DM;
; #pragma unroll
;                 for (int bj = 0; bj < 2; ++bj)
; #pragma unroll
;                     for (int n = 0; n < 2; ++n) { const f32x4 y = __builtin_nontemporal_load((const f32x4*)(x + o + bj * 128 + n * 16)) + acc[ai][bj][m][n]; acc[ai][bj][m][n] = y;
;                         s += (y[0] * y[0] + y[1] * y[1]) + (y[2] * y[2] + y[3] * y[3]); }
;                 s += __shfl_xor(s, 16); s += __shfl_xor(s, 32);
;                 if (fq == 0) P[(ai * 128 + wr * 64 + m * 16 + fr) * 4 + wc] = s; }
.LBB0_796:
	s_lshl_b32 s18, s14, 8
	s_add_i32 s0, s18, s46
	v_or_b32_e32 v128, s0, v146
	v_ashrrev_i32_e32 v129, 31, v128
	v_readlane_b32 s44, v248, 7
	s_lshl_b32 s2, s16, 8
	v_lshlrev_b64 v[128:129], 13, v[128:129]
	v_readlane_b32 s45, v248, 8
	s_ashr_i32 s3, s2, 31
	v_and_b32_e32 v130, 12, v145
	v_lshl_add_u64 v[128:129], s[44:45], 0, v[128:129]
	s_mov_b32 s1, 0
	v_lshl_add_u64 v[128:129], s[2:3], 2, v[128:129]
	s_lshl_b32 s0, s40, 7
	v_lshl_add_u64 v[128:129], v[128:129], 0, s[0:1]
	v_lshlrev_b32_e32 v132, 2, v130
	v_mov_b32_e32 v133, 0
	v_lshl_add_u64 v[128:129], v[128:129], 0, v[132:133]
	s_barrier
	global_load_dwordx4 v[134:137], v[128:129], off nt
	global_load_dwordx4 v[138:141], v[128:129], off offset:64 nt
	global_load_dwordx4 v[146:149], v[128:129], off offset:512 nt
	global_load_dwordx4 v[150:153], v[128:129], off offset:576 nt
	v_add_co_u32_e32 v250, vcc, 0x20000, v128
	s_nop 1
	v_addc_co_u32_e32 v251, vcc, 0, v129, vcc
	global_load_dwordx4 v[188:191], v[250:251], off nt
	global_load_dwordx4 v[192:195], v[250:251], off offset:64 nt
	global_load_dwordx4 v[196:199], v[250:251], off offset:512 nt
	global_load_dwordx4 v[200:203], v[250:251], off offset:576 nt
	v_add_co_u32_e32 v250, vcc, 0x40000, v128
	s_nop 1
	v_addc_co_u32_e32 v251, vcc, 0, v129, vcc
	global_load_dwordx4 v[204:207], v[250:251], off nt
	global_load_dwordx4 v[208:211], v[250:251], off offset:64 nt
	global_load_dwordx4 v[212:215], v[250:251], off offset:512 nt
	global_load_dwordx4 v[216:219], v[250:251], off offset:576 nt
	v_add_co_u32_e32 v250, vcc, 0x60000, v128
	s_nop 1
	v_addc_co_u32_e32 v251, vcc, 0, v129, vcc
	global_load_dwordx4 v[220:223], v[250:251], off nt
	global_load_dwordx4 v[224:227], v[250:251], off offset:64 nt
	global_load_dwordx4 v[228:231], v[250:251], off offset:512 nt
	global_load_dwordx4 v[232:235], v[250:251], off offset:576 nt
	v_add_co_u32_e32 v250, vcc, 0x100000, v128
	s_nop 1
	v_addc_co_u32_e32 v251, vcc, 0, v129, vcc
	global_load_dwordx4 v[236:239], v[250:251], off nt
	global_load_dwordx4 v[240:243], v[250:251], off offset:64 nt
	global_load_dwordx4 v[244:247], v[250:251], off offset:512 nt
	global_load_dwordx4 v[178:181], v[250:251], off offset:576 nt
	v_mbcnt_lo_u32_b32 v132, -1, 0
	v_mbcnt_hi_u32_b32 v133, -1, v132
	v_and_b32_e32 v142, 64, v133
	v_xor_b32_e32 v132, 16, v133
	v_add_u32_e32 v142, 64, v142
	v_cmp_lt_i32_e32 vcc, v132, v142
	s_lshl_b32 s3, s40, 2
	v_and_b32_e32 v131, 63, v186
	v_cndmask_b32_e32 v132, v133, v132, vcc
	v_lshlrev_b32_e32 v132, 2, v132
	s_add_i32 s3, s3, 0
	v_cmp_gt_u32_e64 s[0:1], 16, v131
	v_readlane_b32 s46, v248, 9
	v_readlane_b32 s47, v248, 10
	v_readlane_b32 s48, v248, 11
	v_readlane_b32 s49, v248, 12
	v_readlane_b32 s50, v248, 13
	v_readlane_b32 s51, v248, 14
	v_readlane_b32 s52, v248, 15
	v_readlane_b32 s53, v248, 16
	v_readlane_b32 s54, v248, 17
	v_readlane_b32 s55, v248, 18
	v_readlane_b32 s56, v248, 19
	v_readlane_b32 s57, v248, 20
	v_readlane_b32 s58, v248, 21
	v_readlane_b32 s59, v248, 22
	s_waitcnt vmcnt(16)
	v_pk_add_f32 v[126:127], v[126:127], v[136:137]
	v_pk_add_f32 v[124:125], v[124:125], v[134:135]
	v_pk_add_f32 v[122:123], v[122:123], v[140:141]
	v_pk_add_f32 v[120:121], v[120:121], v[138:139]
	v_pk_add_f32 v[118:119], v[118:119], v[148:149]
	v_pk_add_f32 v[116:117], v[116:117], v[146:147]
	v_mul_f32_e32 v134, v125, v125
	v_mul_f32_e32 v135, v127, v127
	v_mul_f32_e32 v136, v121, v121
	v_mul_f32_e32 v137, v123, v123
	v_pk_add_f32 v[114:115], v[114:115], v[152:153]
	v_pk_add_f32 v[112:113], v[112:113], v[150:151]
	v_mul_f32_e32 v138, v117, v117
	v_mul_f32_e32 v139, v119, v119
	v_fmac_f32_e32 v134, v124, v124
	v_fmac_f32_e32 v135, v126, v126
	v_fmac_f32_e32 v136, v120, v120
	v_fmac_f32_e32 v137, v122, v122
	v_mul_f32_e32 v140, v113, v113
	v_mul_f32_e32 v141, v115, v115
	v_fmac_f32_e32 v138, v116, v116
	v_fmac_f32_e32 v139, v118, v118
	v_add_f32_e32 v134, v134, v135
	v_add_f32_e32 v135, v136, v137
	v_fmac_f32_e32 v140, v112, v112
	v_fmac_f32_e32 v141, v114, v114
	v_add_f32_e32 v136, v138, v139
	v_add_f32_e32 v134, v134, v135
	v_add_f32_e32 v134, v134, v136
	v_add_f32_e32 v135, v140, v141
	v_add_f32_e32 v135, v134, v135
	ds_bpermute_b32 v136, v132, v135
	v_xor_b32_e32 v134, 32, v133
	v_cmp_lt_i32_e32 vcc, v134, v142
	s_waitcnt lgkmcnt(0)
	v_add_f32_e32 v135, v135, v136
	v_cndmask_b32_e32 v133, v133, v134, vcc
	v_lshlrev_b32_e32 v134, 2, v133
	ds_bpermute_b32 v136, v134, v135
	v_lshl_add_u32 v133, v144, 4, s3
	s_and_saveexec_b64 s[4:5], s[0:1]
	s_cbranch_execz .LBB0_798
	s_waitcnt lgkmcnt(0)
	v_add_f32_e32 v135, v135, v136
	ds_write_b32 v133, v135
;     __device__ __forceinline__ void fused(Acc& acc, const Unit& u, int wr, int wc, int fr, int fq, LAS unsigned char* lds, int wid, int lane) const {
;     ...
;             for (int m = 0; m < 4; ++m) { float s = 0.f; const size_t o = o0 + (size_t)(ai * 128 + m * 16) * DM;
; #pragma unroll
;                 for (int bj = 0; bj < 2; ++bj)
; #pragma unroll
;                     for (int n = 0; n < 2; ++n) { const f32x4 y = __builtin_nontemporal_load((const f32x4*)(x + o + bj * 128 + n * 16)) + acc[ai][bj][m][n]; acc[ai][bj][m][n] = y;
;                         s += (y[0] * y[0] + y[1] * y[1]) + (y[2] * y[2] + y[3] * y[3]); }
;                 s += __shfl_xor(s, 16); s += __shfl_xor(s, 32);
;                 if (fq == 0) P[(ai * 128 + wr * 64 + m * 16 + fr) * 4 + wc] = s; }
.LBB0_798:
	s_or_b64 exec, exec, s[4:5]
	v_add_co_u32_e32 v150, vcc, 0x20000, v128
	s_nop 1
	v_addc_co_u32_e32 v151, vcc, 0, v129, vcc
	s_waitcnt lgkmcnt(0)
	s_nop 0
	s_waitcnt vmcnt(12)
	v_mov_b32_e32 v136, v188
	v_mov_b32_e32 v137, v189
	v_mov_b32_e32 v138, v190
	v_mov_b32_e32 v139, v191
	v_mov_b32_e32 v140, v192
	v_mov_b32_e32 v141, v193
	v_mov_b32_e32 v142, v194
	v_mov_b32_e32 v143, v195
	v_mov_b32_e32 v146, v196
	v_mov_b32_e32 v147, v197
	v_mov_b32_e32 v148, v198
	v_mov_b32_e32 v149, v199
	v_mov_b32_e32 v150, v200
	v_mov_b32_e32 v151, v201
	v_mov_b32_e32 v152, v202
	v_mov_b32_e32 v153, v203
	v_add_co_u32_e32 v250, vcc, 0x120000, v128
	s_nop 1
	v_addc_co_u32_e32 v251, vcc, 0, v129, vcc
	global_load_dwordx4 v[188:191], v[250:251], off nt
	global_load_dwordx4 v[192:195], v[250:251], off offset:64 nt
	global_load_dwordx4 v[196:199], v[250:251], off offset:512 nt
	global_load_dwordx4 v[200:203], v[250:251], off offset:576 nt
	v_pk_add_f32 v[110:111], v[110:111], v[138:139]
	v_pk_add_f32 v[108:109], v[108:109], v[136:137]
	v_pk_add_f32 v[106:107], v[106:107], v[142:143]
	v_pk_add_f32 v[104:105], v[104:105], v[140:141]
	v_pk_add_f32 v[102:103], v[102:103], v[148:149]
	v_pk_add_f32 v[100:101], v[100:101], v[146:147]
	v_mul_f32_e32 v135, v109, v109
	v_mul_f32_e32 v136, v111, v111
	v_mul_f32_e32 v137, v105, v105
	v_mul_f32_e32 v138, v107, v107
	v_pk_add_f32 v[98:99], v[98:99], v[152:153]
	v_pk_add_f32 v[96:97], v[96:97], v[150:151]
	v_mul_f32_e32 v139, v101, v101
	v_mul_f32_e32 v140, v103, v103
	v_fmac_f32_e32 v135, v108, v108
	v_fmac_f32_e32 v136, v110, v110
	v_fmac_f32_e32 v137, v104, v104
	v_fmac_f32_e32 v138, v106, v106
	v_mul_f32_e32 v141, v97, v97
	v_mul_f32_e32 v142, v99, v99
	v_fmac_f32_e32 v139, v100, v100
	v_fmac_f32_e32 v140, v102, v102
	v_add_f32_e32 v135, v135, v136
	v_add_f32_e32 v136, v137, v138
	v_fmac_f32_e32 v141, v96, v96
	v_fmac_f32_e32 v142, v98, v98
	v_add_f32_e32 v137, v139, v140
	v_add_f32_e32 v135, v135, v136
	v_add_f32_e32 v135, v135, v137
	v_add_f32_e32 v136, v141, v142
	v_add_f32_e32 v135, v135, v136
	ds_bpermute_b32 v136, v132, v135
	s_waitcnt lgkmcnt(0)
	v_add_f32_e32 v135, v135, v136
	ds_bpermute_b32 v136, v134, v135
	s_and_saveexec_b64 s[4:5], s[0:1]
	s_cbranch_execz .LBB0_800
	s_waitcnt lgkmcnt(0)
	v_add_f32_e32 v135, v135, v136
	ds_write_b32 v133, v135 offset:256
.LBB0_800:
	s_or_b64 exec, exec, s[4:5]
	v_add_co_u32_e32 v150, vcc, 0x40000, v128
	s_nop 1
	v_addc_co_u32_e32 v151, vcc, 0, v129, vcc
	s_waitcnt lgkmcnt(0)
	s_nop 0
	s_waitcnt vmcnt(12)
	v_mov_b32_e32 v136, v204
	v_mov_b32_e32 v137, v205
	v_mov_b32_e32 v138, v206
	v_mov_b32_e32 v139, v207
	v_mov_b32_e32 v140, v208
	v_mov_b32_e32 v141, v209
	v_mov_b32_e32 v142, v210
	v_mov_b32_e32 v143, v211
	v_mov_b32_e32 v146, v212
	v_mov_b32_e32 v147, v213
	v_mov_b32_e32 v148, v214
	v_mov_b32_e32 v149, v215
	v_mov_b32_e32 v150, v216
	v_mov_b32_e32 v151, v217
	v_mov_b32_e32 v152, v218
	v_mov_b32_e32 v153, v219
	v_add_co_u32_e32 v250, vcc, 0x140000, v128
	s_nop 1
	v_addc_co_u32_e32 v251, vcc, 0, v129, vcc
	global_load_dwordx4 v[204:207], v[250:251], off nt
	global_load_dwordx4 v[208:211], v[250:251], off offset:64 nt
	global_load_dwordx4 v[212:215], v[250:251], off offset:512 nt
	global_load_dwordx4 v[216:219], v[250:251], off offset:576 nt
	v_pk_add_f32 v[94:95], v[94:95], v[138:139]
	v_pk_add_f32 v[92:93], v[92:93], v[136:137]
	v_pk_add_f32 v[90:91], v[90:91], v[142:143]
	v_pk_add_f32 v[88:89], v[88:89], v[140:141]
	v_pk_add_f32 v[86:87], v[86:87], v[148:149]
	v_pk_add_f32 v[84:85], v[84:85], v[146:147]
	v_mul_f32_e32 v135, v93, v93
	v_mul_f32_e32 v136, v95, v95
	v_mul_f32_e32 v137, v89, v89
	v_mul_f32_e32 v138, v91, v91
	v_pk_add_f32 v[82:83], v[82:83], v[152:153]
	v_pk_add_f32 v[80:81], v[80:81], v[150:151]
	v_mul_f32_e32 v139, v85, v85
	v_mul_f32_e32 v140, v87, v87
	v_fmac_f32_e32 v135, v92, v92
	v_fmac_f32_e32 v136, v94, v94
	v_fmac_f32_e32 v137, v88, v88
	v_fmac_f32_e32 v138, v90, v90
	v_mul_f32_e32 v141, v81, v81
	v_mul_f32_e32 v142, v83, v83
	v_fmac_f32_e32 v139, v84, v84
	v_fmac_f32_e32 v140, v86, v86
	v_add_f32_e32 v135, v135, v136
	v_add_f32_e32 v136, v137, v138
	v_fmac_f32_e32 v141, v80, v80
	v_fmac_f32_e32 v142, v82, v82
	v_add_f32_e32 v137, v139, v140
	v_add_f32_e32 v135, v135, v136
	v_add_f32_e32 v135, v135, v137
	v_add_f32_e32 v136, v141, v142
	v_add_f32_e32 v135, v135, v136
	ds_bpermute_b32 v136, v132, v135
	s_waitcnt lgkmcnt(0)
	v_add_f32_e32 v135, v135, v136
	ds_bpermute_b32 v136, v134, v135
	s_and_saveexec_b64 s[4:5], s[0:1]
	s_cbranch_execz .LBB0_802
	s_waitcnt lgkmcnt(0)
	v_add_f32_e32 v135, v135, v136
	ds_write_b32 v133, v135 offset:512
;     __device__ __forceinline__ void fused(Acc& acc, const Unit& u, int wr, int wc, int fr, int fq, LAS unsigned char* lds, int wid, int lane) const {
;     ...
;             for (int m = 0; m < 4; ++m) { float s = 0.f; const size_t o = o0 + (size_t)(ai * 128 + m * 16) * DM;
; #pragma unroll
;                 for (int bj = 0; bj < 2; ++bj)
; #pragma unroll
;                     for (int n = 0; n < 2; ++n) { const f32x4 y = __builtin_nontemporal_load((const f32x4*)(x + o + bj * 128 + n * 16)) + acc[ai][bj][m][n]; acc[ai][bj][m][n] = y;
;                         s += (y[0] * y[0] + y[1] * y[1]) + (y[2] * y[2] + y[3] * y[3]); }
;                 s += __shfl_xor(s, 16); s += __shfl_xor(s, 32);
;                 if (fq == 0) P[(ai * 128 + wr * 64 + m * 16 + fr) * 4 + wc] = s; }
.LBB0_802:
	s_or_b64 exec, exec, s[4:5]
	v_add_co_u32_e32 v150, vcc, 0x60000, v128
	s_nop 1
	v_addc_co_u32_e32 v151, vcc, 0, v129, vcc
	s_waitcnt lgkmcnt(0)
	s_nop 0
	s_waitcnt vmcnt(12)
	v_mov_b32_e32 v136, v220
	v_mov_b32_e32 v137, v221
	v_mov_b32_e32 v138, v222
	v_mov_b32_e32 v139, v223
	v_mov_b32_e32 v140, v224
	v_mov_b32_e32 v141, v225
	v_mov_b32_e32 v142, v226
	v_mov_b32_e32 v143, v227
	v_mov_b32_e32 v146, v228
	v_mov_b32_e32 v147, v229
	v_mov_b32_e32 v148, v230
	v_mov_b32_e32 v149, v231
	v_mov_b32_e32 v150, v232
	v_mov_b32_e32 v151, v233
	v_mov_b32_e32 v152, v234
	v_mov_b32_e32 v153, v235
	v_add_co_u32_e32 v250, vcc, 0x160000, v128
	s_nop 1
	v_addc_co_u32_e32 v251, vcc, 0, v129, vcc
	global_load_dwordx4 v[220:223], v[250:251], off nt
	global_load_dwordx4 v[224:227], v[250:251], off offset:64 nt
	global_load_dwordx4 v[228:231], v[250:251], off offset:512 nt
	global_load_dwordx4 v[232:235], v[250:251], off offset:576 nt
	v_pk_add_f32 v[78:79], v[78:79], v[138:139]
	v_pk_add_f32 v[76:77], v[76:77], v[136:137]
	v_pk_add_f32 v[74:75], v[74:75], v[142:143]
	v_pk_add_f32 v[72:73], v[72:73], v[140:141]
	v_pk_add_f32 v[70:71], v[70:71], v[148:149]
	v_pk_add_f32 v[68:69], v[68:69], v[146:147]
	v_mul_f32_e32 v135, v77, v77
	v_mul_f32_e32 v136, v79, v79
	v_mul_f32_e32 v137, v73, v73
	v_mul_f32_e32 v138, v75, v75
	v_pk_add_f32 v[66:67], v[66:67], v[152:153]
	v_pk_add_f32 v[64:65], v[64:65], v[150:151]
	v_mul_f32_e32 v139, v69, v69
	v_mul_f32_e32 v140, v71, v71
	v_fmac_f32_e32 v135, v76, v76
	v_fmac_f32_e32 v136, v78, v78
	v_fmac_f32_e32 v137, v72, v72
	v_fmac_f32_e32 v138, v74, v74
	v_mul_f32_e32 v141, v65, v65
	v_mul_f32_e32 v142, v67, v67
	v_fmac_f32_e32 v139, v68, v68
	v_fmac_f32_e32 v140, v70, v70
	v_add_f32_e32 v135, v135, v136
	v_add_f32_e32 v136, v137, v138
	v_fmac_f32_e32 v141, v64, v64
	v_fmac_f32_e32 v142, v66, v66
	v_add_f32_e32 v137, v139, v140
	v_add_f32_e32 v135, v135, v136
	v_add_f32_e32 v135, v135, v137
	v_add_f32_e32 v136, v141, v142
	v_add_f32_e32 v135, v135, v136
	ds_bpermute_b32 v136, v132, v135
	s_waitcnt lgkmcnt(0)
	v_add_f32_e32 v135, v135, v136
	ds_bpermute_b32 v136, v134, v135
	s_and_saveexec_b64 s[4:5], s[0:1]
	s_cbranch_execz .LBB0_804
	s_waitcnt lgkmcnt(0)
	v_add_f32_e32 v135, v135, v136
	ds_write_b32 v133, v135 offset:768
.LBB0_804:
	s_or_b64 exec, exec, s[4:5]
	v_add_co_u32_e32 v150, vcc, 0x100000, v128
	s_nop 1
	v_addc_co_u32_e32 v151, vcc, 0, v129, vcc
	s_waitcnt lgkmcnt(0)
	s_nop 0
	s_waitcnt vmcnt(12)
	v_mov_b32_e32 v136, v236
	v_mov_b32_e32 v137, v237
	v_mov_b32_e32 v138, v238
	v_mov_b32_e32 v139, v239
	v_mov_b32_e32 v140, v240
	v_mov_b32_e32 v141, v241
	v_mov_b32_e32 v142, v242
	v_mov_b32_e32 v143, v243
	v_mov_b32_e32 v146, v244
	v_mov_b32_e32 v147, v245
	v_mov_b32_e32 v148, v246
	v_mov_b32_e32 v149, v247
	v_mov_b32_e32 v150, v178
	v_mov_b32_e32 v151, v179
	v_mov_b32_e32 v152, v180
	v_mov_b32_e32 v153, v181
	v_pk_add_f32 v[62:63], v[62:63], v[138:139]
	v_pk_add_f32 v[60:61], v[60:61], v[136:137]
	v_pk_add_f32 v[58:59], v[58:59], v[142:143]
	v_pk_add_f32 v[56:57], v[56:57], v[140:141]
	v_pk_add_f32 v[54:55], v[54:55], v[148:149]
	v_pk_add_f32 v[52:53], v[52:53], v[146:147]
	v_mul_f32_e32 v135, v61, v61
	v_mul_f32_e32 v136, v63, v63
	v_mul_f32_e32 v137, v57, v57
	v_mul_f32_e32 v138, v59, v59
	v_pk_add_f32 v[50:51], v[50:51], v[152:153]
	v_pk_add_f32 v[48:49], v[48:49], v[150:151]
	v_mul_f32_e32 v139, v53, v53
	v_mul_f32_e32 v140, v55, v55
	v_fmac_f32_e32 v135, v60, v60
	v_fmac_f32_e32 v136, v62, v62
	v_fmac_f32_e32 v137, v56, v56
	v_fmac_f32_e32 v138, v58, v58
	v_mul_f32_e32 v141, v49, v49
	v_mul_f32_e32 v142, v51, v51
	v_fmac_f32_e32 v139, v52, v52
	v_fmac_f32_e32 v140, v54, v54
	v_add_f32_e32 v135, v135, v136
	v_add_f32_e32 v136, v137, v138
	v_fmac_f32_e32 v141, v48, v48
	v_fmac_f32_e32 v142, v50, v50
	v_add_f32_e32 v137, v139, v140
	v_add_f32_e32 v135, v135, v136
	v_add_f32_e32 v135, v135, v137
	v_add_f32_e32 v136, v141, v142
	v_add_f32_e32 v135, v135, v136
	ds_bpermute_b32 v136, v132, v135
	s_waitcnt lgkmcnt(0)
	v_add_f32_e32 v136, v135, v136
	ds_bpermute_b32 v137, v134, v136
	v_add_u32_e32 v135, 0x80, v144
	s_and_saveexec_b64 s[4:5], s[0:1]
	s_cbranch_execz .LBB0_806
	v_lshl_add_u32 v138, v135, 4, s3
	s_waitcnt lgkmcnt(0)
	v_add_f32_e32 v136, v136, v137
	ds_write_b32 v138, v136
;     __device__ __forceinline__ void fused(Acc& acc, const Unit& u, int wr, int wc, int fr, int fq, LAS unsigned char* lds, int wid, int lane) const {
;     ...
;             for (int m = 0; m < 4; ++m) { float s = 0.f; const size_t o = o0 + (size_t)(ai * 128 + m * 16) * DM;
; #pragma unroll
;                 for (int bj = 0; bj < 2; ++bj)
; #pragma unroll
;                     for (int n = 0; n < 2; ++n) { const f32x4 y = __builtin_nontemporal_load((const f32x4*)(x + o + bj * 128 + n * 16)) + acc[ai][bj][m][n]; acc[ai][bj][m][n] = y;
;                         s += (y[0] * y[0] + y[1] * y[1]) + (y[2] * y[2] + y[3] * y[3]); }
;                 s += __shfl_xor(s, 16); s += __shfl_xor(s, 32);
;                 if (fq == 0) P[(ai * 128 + wr * 64 + m * 16 + fr) * 4 + wc] = s; }
.LBB0_806:
	s_or_b64 exec, exec, s[4:5]
	v_add_co_u32_e32 v150, vcc, 0x120000, v128
	s_nop 1
	v_addc_co_u32_e32 v151, vcc, 0, v129, vcc
	s_waitcnt lgkmcnt(0)
	s_nop 0
	s_waitcnt vmcnt(8)
	v_mov_b32_e32 v136, v188
	v_mov_b32_e32 v137, v189
	v_mov_b32_e32 v138, v190
	v_mov_b32_e32 v139, v191
	v_mov_b32_e32 v140, v192
	v_mov_b32_e32 v141, v193
	v_mov_b32_e32 v142, v194
	v_mov_b32_e32 v143, v195
	v_mov_b32_e32 v146, v196
	v_mov_b32_e32 v147, v197
	v_mov_b32_e32 v148, v198
	v_mov_b32_e32 v149, v199
	v_mov_b32_e32 v150, v200
	v_mov_b32_e32 v151, v201
	v_mov_b32_e32 v152, v202
	v_mov_b32_e32 v153, v203
	v_pk_add_f32 v[46:47], v[46:47], v[138:139]
	v_pk_add_f32 v[44:45], v[44:45], v[136:137]
	v_pk_add_f32 v[42:43], v[42:43], v[142:143]
	v_pk_add_f32 v[40:41], v[40:41], v[140:141]
	v_pk_add_f32 v[38:39], v[38:39], v[148:149]
	v_pk_add_f32 v[36:37], v[36:37], v[146:147]
	v_mul_f32_e32 v136, v45, v45
	v_mul_f32_e32 v137, v47, v47
	v_mul_f32_e32 v138, v41, v41
	v_mul_f32_e32 v139, v43, v43
	v_pk_add_f32 v[34:35], v[34:35], v[152:153]
	v_pk_add_f32 v[32:33], v[32:33], v[150:151]
	v_mul_f32_e32 v140, v37, v37
	v_mul_f32_e32 v141, v39, v39
	v_fmac_f32_e32 v136, v44, v44
	v_fmac_f32_e32 v137, v46, v46
	v_fmac_f32_e32 v138, v40, v40
	v_fmac_f32_e32 v139, v42, v42
	v_mul_f32_e32 v142, v33, v33
	v_mul_f32_e32 v143, v35, v35
	v_fmac_f32_e32 v140, v36, v36
	v_fmac_f32_e32 v141, v38, v38
	v_add_f32_e32 v136, v136, v137
	v_add_f32_e32 v137, v138, v139
	v_fmac_f32_e32 v142, v32, v32
	v_fmac_f32_e32 v143, v34, v34
	v_add_f32_e32 v138, v140, v141
	v_add_f32_e32 v136, v136, v137
	v_add_f32_e32 v136, v136, v138
	v_add_f32_e32 v137, v142, v143
	v_add_f32_e32 v136, v136, v137
	ds_bpermute_b32 v137, v132, v136
	s_waitcnt lgkmcnt(0)
	v_add_f32_e32 v136, v136, v137
	ds_bpermute_b32 v137, v134, v136
	s_and_saveexec_b64 s[4:5], s[0:1]
	s_cbranch_execz .LBB0_808
	s_waitcnt lgkmcnt(0)
	v_add_f32_e32 v136, v136, v137
	ds_write_b32 v133, v136 offset:2304
.LBB0_808:
	s_or_b64 exec, exec, s[4:5]
	v_add_co_u32_e32 v150, vcc, 0x140000, v128
	s_nop 1
	v_addc_co_u32_e32 v151, vcc, 0, v129, vcc
	s_waitcnt lgkmcnt(0)
	s_nop 0
	s_waitcnt vmcnt(4)
	v_mov_b32_e32 v136, v204
	v_mov_b32_e32 v137, v205
	v_mov_b32_e32 v138, v206
	v_mov_b32_e32 v139, v207
	v_mov_b32_e32 v140, v208
	v_mov_b32_e32 v141, v209
	v_mov_b32_e32 v142, v210
	v_mov_b32_e32 v143, v211
	v_mov_b32_e32 v146, v212
	v_mov_b32_e32 v147, v213
	v_mov_b32_e32 v148, v214
	v_mov_b32_e32 v149, v215
	v_mov_b32_e32 v150, v216
	v_mov_b32_e32 v151, v217
	v_mov_b32_e32 v152, v218
	v_mov_b32_e32 v153, v219
	v_pk_add_f32 v[30:31], v[30:31], v[138:139]
	v_pk_add_f32 v[28:29], v[28:29], v[136:137]
	v_pk_add_f32 v[26:27], v[26:27], v[142:143]
	v_pk_add_f32 v[24:25], v[24:25], v[140:141]
	v_pk_add_f32 v[22:23], v[22:23], v[148:149]
	v_pk_add_f32 v[20:21], v[20:21], v[146:147]
	v_mul_f32_e32 v136, v29, v29
	v_mul_f32_e32 v137, v31, v31
	v_mul_f32_e32 v138, v25, v25
	v_mul_f32_e32 v139, v27, v27
	v_pk_add_f32 v[18:19], v[18:19], v[152:153]
	v_pk_add_f32 v[16:17], v[16:17], v[150:151]
	v_mul_f32_e32 v140, v21, v21
	v_mul_f32_e32 v141, v23, v23
	v_fmac_f32_e32 v136, v28, v28
	v_fmac_f32_e32 v137, v30, v30
	v_fmac_f32_e32 v138, v24, v24
	v_fmac_f32_e32 v139, v26, v26
	v_mul_f32_e32 v142, v17, v17
	v_mul_f32_e32 v143, v19, v19
	v_fmac_f32_e32 v140, v20, v20
	v_fmac_f32_e32 v141, v22, v22
	v_add_f32_e32 v136, v136, v137
	v_add_f32_e32 v137, v138, v139
	v_fmac_f32_e32 v142, v16, v16
	v_fmac_f32_e32 v143, v18, v18
	v_add_f32_e32 v138, v140, v141
	v_add_f32_e32 v136, v136, v137
	v_add_f32_e32 v136, v136, v138
	v_add_f32_e32 v137, v142, v143
	v_add_f32_e32 v136, v136, v137
	ds_bpermute_b32 v137, v132, v136
	s_waitcnt lgkmcnt(0)
	v_add_f32_e32 v136, v136, v137
	ds_bpermute_b32 v137, v134, v136
	s_and_saveexec_b64 s[4:5], s[0:1]
	s_cbranch_execz .LBB0_810
	s_waitcnt lgkmcnt(0)
	v_add_f32_e32 v136, v136, v137
	ds_write_b32 v133, v136 offset:2560
.LBB0_810:
	s_or_b64 exec, exec, s[4:5]
	v_add_co_u32_e32 v128, vcc, 0x160000, v128
	s_nop 1
	v_addc_co_u32_e32 v129, vcc, 0, v129, vcc
	s_waitcnt lgkmcnt(0)
	s_waitcnt vmcnt(0)
	v_mov_b32_e32 v136, v220
	v_mov_b32_e32 v137, v221
	v_mov_b32_e32 v138, v222
	v_mov_b32_e32 v139, v223
	v_mov_b32_e32 v140, v224
	v_mov_b32_e32 v141, v225
	v_mov_b32_e32 v142, v226
	v_mov_b32_e32 v143, v227
	v_mov_b32_e32 v146, v228
	v_mov_b32_e32 v147, v229
	v_mov_b32_e32 v148, v230
	v_mov_b32_e32 v149, v231
	v_mov_b32_e32 v150, v232
	v_mov_b32_e32 v151, v233
	v_mov_b32_e32 v152, v234
	v_mov_b32_e32 v153, v235
	v_pk_add_f32 v[14:15], v[14:15], v[138:139]
	v_pk_add_f32 v[12:13], v[12:13], v[136:137]
	v_pk_add_f32 v[10:11], v[10:11], v[142:143]
	v_pk_add_f32 v[8:9], v[8:9], v[140:141]
	v_pk_add_f32 v[6:7], v[6:7], v[148:149]
	v_pk_add_f32 v[4:5], v[4:5], v[146:147]
	v_mul_f32_e32 v128, v13, v13
	v_mul_f32_e32 v129, v15, v15
	v_mul_f32_e32 v136, v9, v9
	v_mul_f32_e32 v137, v11, v11
	v_pk_add_f32 v[2:3], v[2:3], v[152:153]
	v_pk_add_f32 v[0:1], v[0:1], v[150:151]
	v_mul_f32_e32 v138, v5, v5
	v_mul_f32_e32 v139, v7, v7
	v_fmac_f32_e32 v128, v12, v12
	v_fmac_f32_e32 v129, v14, v14
	v_fmac_f32_e32 v136, v8, v8
	v_fmac_f32_e32 v137, v10, v10
	v_mul_f32_e32 v140, v1, v1
	v_mul_f32_e32 v141, v3, v3
	v_fmac_f32_e32 v138, v4, v4
	v_fmac_f32_e32 v139, v6, v6
	v_add_f32_e32 v128, v128, v129
	v_add_f32_e32 v129, v136, v137
	v_fmac_f32_e32 v140, v0, v0
	v_fmac_f32_e32 v141, v2, v2
	v_add_f32_e32 v136, v138, v139
	v_add_f32_e32 v128, v128, v129
	v_add_f32_e32 v128, v128, v136
	v_add_f32_e32 v129, v140, v141
	v_add_f32_e32 v128, v128, v129
	ds_bpermute_b32 v129, v132, v128
	s_waitcnt lgkmcnt(0)
	v_add_f32_e32 v128, v128, v129
	ds_bpermute_b32 v129, v134, v128
	s_and_saveexec_b64 s[4:5], s[0:1]
	s_cbranch_execz .LBB0_812
	s_waitcnt lgkmcnt(0)
	v_add_f32_e32 v128, v128, v129
	ds_write_b32 v133, v128 offset:2816
